# hand-written B_in gelu epilogue: packed f32 math, folded gelu constants, in-place bf16 pack
# speedup vs baseline: 1.0649x; 1.0112x over previous
.LBB0_599:
	ds_read_b128 v[140:143], v149
	v_xor_b32_e32 v179, 64, v149
	ds_read_b128 v[154:157], v179
	ds_read_b128 v[158:161], v149 offset:2048
	ds_read_b128 v[176:179], v179 offset:2048
	s_add_u32 s28, s26, 0xfff80080
	s_addc_u32 s29, s27, -1
	s_cmp_eq_u32 s49, 28
	s_cselect_b32 s31, s1, s29
	s_cselect_b32 s30, s13, s28
	s_cselect_b32 s29, s19, s48
	s_cselect_b32 s28, s21, s33
	v_lshl_add_u64 v[144:145], s[26:27], 0, v[132:133]
	s_add_i32 m0, s37, 0xc000
	ds_read_b128 v[180:183], v150
	v_xor_b32_e32 v211, 64, v150
	ds_read_b128 v[184:187], v211
	ds_read_b128 v[188:191], v150 offset:2048
	ds_read_b128 v[192:195], v211 offset:2048
	ds_read_b128 v[196:199], v150 offset:4096
	ds_read_b128 v[200:203], v211 offset:4096
	ds_read_b128 v[204:207], v150 offset:6144
	ds_read_b128 v[208:211], v211 offset:6144
	global_load_lds_dwordx4 v[144:145], off
	v_lshl_add_u64 v[144:145], s[26:27], 0, v[134:135]
	s_add_i32 m0, s37, 0xe000
	s_nop 0
	global_load_lds_dwordx4 v[144:145], off
	s_waitcnt lgkmcnt(8)
	s_barrier
	s_waitcnt lgkmcnt(0)
	s_setprio 1
	s_waitcnt lgkmcnt(0)
	v_mfma_f32_16x16x32_bf16 v[124:127], v[140:143], v[180:183], v[124:127]
	v_mfma_f32_16x16x32_bf16 v[124:127], v[154:157], v[184:187], v[124:127]
	v_mfma_f32_16x16x32_bf16 v[120:123], v[176:179], v[184:187], v[120:123]
	v_mfma_f32_16x16x32_bf16 v[120:123], v[158:161], v[180:183], v[120:123]
	v_mfma_f32_16x16x32_bf16 v[104:107], v[158:161], v[188:191], v[104:107]
	v_mfma_f32_16x16x32_bf16 v[104:107], v[176:179], v[192:195], v[104:107]
	v_mfma_f32_16x16x32_bf16 v[108:111], v[154:157], v[192:195], v[108:111]
	v_mfma_f32_16x16x32_bf16 v[108:111], v[140:143], v[188:191], v[108:111]
	v_mfma_f32_16x16x32_bf16 v[92:95], v[140:143], v[196:199], v[92:95]
	v_mfma_f32_16x16x32_bf16 v[92:95], v[154:157], v[200:203], v[92:95]
	v_mfma_f32_16x16x32_bf16 v[88:91], v[176:179], v[200:203], v[88:91]
	v_mfma_f32_16x16x32_bf16 v[88:91], v[158:161], v[196:199], v[88:91]
	v_mfma_f32_16x16x32_bf16 v[72:75], v[158:161], v[204:207], v[72:75]
	v_mfma_f32_16x16x32_bf16 v[72:75], v[176:179], v[208:211], v[72:75]
	v_mfma_f32_16x16x32_bf16 v[76:79], v[154:157], v[208:211], v[76:79]
	v_mfma_f32_16x16x32_bf16 v[76:79], v[140:143], v[204:207], v[76:79]
	s_setprio 0
	s_barrier
	s_add_i32 s52, s46, s36
	v_lshl_add_u64 v[144:145], s[28:29], 0, v[164:165]
	s_mov_b32 m0, s52
	ds_read_b128 v[212:215], v151
	v_xor_b32_e32 v251, 64, v151
	ds_read_b128 v[240:243], v251
	ds_read_b128 v[244:247], v151 offset:2048
	ds_read_b128 v[248:251], v251 offset:2048
	global_load_lds_dwordx4 v[144:145], off
	v_lshl_add_u64 v[216:217], s[28:29], 0, v[166:167]
	s_add_i32 m0, s52, 0x2000
	s_nop 0
	global_load_lds_dwordx4 v[216:217], off
	s_barrier
	s_waitcnt lgkmcnt(0)
	s_setprio 1
	s_waitcnt lgkmcnt(0)
	v_mfma_f32_16x16x32_bf16 v[116:119], v[212:215], v[180:183], v[116:119]
	v_mfma_f32_16x16x32_bf16 v[116:119], v[240:243], v[184:187], v[116:119]
	v_mfma_f32_16x16x32_bf16 v[112:115], v[248:251], v[184:187], v[112:115]
	v_mfma_f32_16x16x32_bf16 v[112:115], v[244:247], v[180:183], v[112:115]
	v_mfma_f32_16x16x32_bf16 v[96:99], v[244:247], v[188:191], v[96:99]
	v_mfma_f32_16x16x32_bf16 v[96:99], v[248:251], v[192:195], v[96:99]
	v_mfma_f32_16x16x32_bf16 v[100:103], v[240:243], v[192:195], v[100:103]
	v_mfma_f32_16x16x32_bf16 v[100:103], v[212:215], v[188:191], v[100:103]
	v_mfma_f32_16x16x32_bf16 v[84:87], v[212:215], v[196:199], v[84:87]
	v_mfma_f32_16x16x32_bf16 v[84:87], v[240:243], v[200:203], v[84:87]
	v_mfma_f32_16x16x32_bf16 v[80:83], v[248:251], v[200:203], v[80:83]
	v_mfma_f32_16x16x32_bf16 v[80:83], v[244:247], v[196:199], v[80:83]
	v_mfma_f32_16x16x32_bf16 v[64:67], v[244:247], v[204:207], v[64:67]
	v_mfma_f32_16x16x32_bf16 v[64:67], v[248:251], v[208:211], v[64:67]
	v_mfma_f32_16x16x32_bf16 v[68:71], v[240:243], v[208:211], v[68:71]
	v_mfma_f32_16x16x32_bf16 v[68:71], v[212:215], v[204:207], v[68:71]
	s_setprio 0
	s_mov_b32 m0, s37
	v_lshl_add_u64 v[252:253], s[30:31], 0, v[128:129]
	s_barrier
	ds_read_b128 v[180:183], v150 offset:16384
	v_xor_b32_e32 v211, 64, v150
	ds_read_b128 v[184:187], v211 offset:16384
	ds_read_b128 v[188:191], v150 offset:18432
	ds_read_b128 v[192:195], v211 offset:18432
	ds_read_b128 v[196:199], v150 offset:20480
	ds_read_b128 v[200:203], v211 offset:20480
	ds_read_b128 v[204:207], v150 offset:22528
	ds_read_b128 v[208:211], v211 offset:22528
	global_load_lds_dwordx4 v[252:253], off
	v_lshl_add_u64 v[234:235], s[30:31], 0, v[130:131]
	s_mov_b32 m0, s38
	s_nop 0
	global_load_lds_dwordx4 v[234:235], off
	s_barrier
	s_waitcnt lgkmcnt(0)
	s_setprio 1
	s_waitcnt lgkmcnt(0)
	v_mfma_f32_16x16x32_bf16 v[60:63], v[140:143], v[180:183], v[60:63]
	v_mfma_f32_16x16x32_bf16 v[60:63], v[154:157], v[184:187], v[60:63]
	v_mfma_f32_16x16x32_bf16 v[56:59], v[176:179], v[184:187], v[56:59]
	v_mfma_f32_16x16x32_bf16 v[56:59], v[158:161], v[180:183], v[56:59]
	v_mfma_f32_16x16x32_bf16 v[40:43], v[158:161], v[188:191], v[40:43]
	v_mfma_f32_16x16x32_bf16 v[40:43], v[176:179], v[192:195], v[40:43]
	v_mfma_f32_16x16x32_bf16 v[44:47], v[154:157], v[192:195], v[44:47]
	v_mfma_f32_16x16x32_bf16 v[44:47], v[140:143], v[188:191], v[44:47]
	v_mfma_f32_16x16x32_bf16 v[28:31], v[140:143], v[196:199], v[28:31]
	v_mfma_f32_16x16x32_bf16 v[28:31], v[154:157], v[200:203], v[28:31]
	v_mfma_f32_16x16x32_bf16 v[24:27], v[176:179], v[200:203], v[24:27]
	v_mfma_f32_16x16x32_bf16 v[24:27], v[158:161], v[196:199], v[24:27]
	v_mfma_f32_16x16x32_bf16 v[8:11], v[158:161], v[204:207], v[8:11]
	v_mfma_f32_16x16x32_bf16 v[8:11], v[176:179], v[208:211], v[8:11]
	v_mfma_f32_16x16x32_bf16 v[12:15], v[154:157], v[208:211], v[12:15]
	v_mfma_f32_16x16x32_bf16 v[12:15], v[140:143], v[204:207], v[12:15]
	s_setprio 0
	s_barrier
	s_add_u32 s52, s28, 0x80000
	s_addc_u32 s53, s29, 0
	s_add_i32 s54, s47, s36
	v_lshl_add_u64 v[140:141], s[52:53], 0, v[164:165]
	s_mov_b32 m0, s54
	s_nop 0
	global_load_lds_dwordx4 v[140:141], off
	v_lshl_add_u64 v[140:141], s[52:53], 0, v[166:167]
	s_add_i32 m0, s54, 0x2000
	s_nop 0
	global_load_lds_dwordx4 v[140:141], off
	s_waitcnt vmcnt(6)
	s_barrier
	s_setprio 1
	v_mfma_f32_16x16x32_bf16 v[52:55], v[212:215], v[180:183], v[52:55]
	v_mfma_f32_16x16x32_bf16 v[52:55], v[240:243], v[184:187], v[52:55]
	v_mfma_f32_16x16x32_bf16 v[48:51], v[248:251], v[184:187], v[48:51]
	v_mfma_f32_16x16x32_bf16 v[48:51], v[244:247], v[180:183], v[48:51]
	v_mfma_f32_16x16x32_bf16 v[32:35], v[244:247], v[188:191], v[32:35]
	v_mfma_f32_16x16x32_bf16 v[32:35], v[248:251], v[192:195], v[32:35]
	v_mfma_f32_16x16x32_bf16 v[36:39], v[240:243], v[192:195], v[36:39]
	v_mfma_f32_16x16x32_bf16 v[36:39], v[212:215], v[188:191], v[36:39]
	v_mfma_f32_16x16x32_bf16 v[20:23], v[212:215], v[196:199], v[20:23]
	v_mfma_f32_16x16x32_bf16 v[20:23], v[240:243], v[200:203], v[20:23]
	v_mfma_f32_16x16x32_bf16 v[16:19], v[248:251], v[200:203], v[16:19]
	v_mfma_f32_16x16x32_bf16 v[16:19], v[244:247], v[196:199], v[16:19]
	v_mfma_f32_16x16x32_bf16 v[0:3], v[244:247], v[204:207], v[0:3]
	v_mfma_f32_16x16x32_bf16 v[0:3], v[248:251], v[208:211], v[0:3]
	v_mfma_f32_16x16x32_bf16 v[4:7], v[240:243], v[208:211], v[4:7]
	v_mfma_f32_16x16x32_bf16 v[4:7], v[212:215], v[204:207], v[4:7]
	s_setprio 0
	s_add_i32 s52, 0, 0x18000
	v_add_u32_e32 v169, s52, v147
	s_barrier
	ds_read_b128 v[140:143], v169
	v_xor_b32_e32 v179, 64, v169
	ds_read_b128 v[154:157], v179
	ds_read_b128 v[158:161], v169 offset:2048
	ds_read_b128 v[176:179], v179 offset:2048
	s_add_u32 s30, s30, 0x80000
	s_addc_u32 s31, s31, 0
	s_mov_b32 m0, s39
	v_lshl_add_u64 v[212:213], s[30:31], 0, v[128:129]
	ds_read_b128 v[180:183], v150 offset:32768
	v_xor_b32_e32 v211, 64, v150
	ds_read_b128 v[184:187], v211 offset:32768
	ds_read_b128 v[188:191], v150 offset:34816
	ds_read_b128 v[192:195], v211 offset:34816
	ds_read_b128 v[196:199], v150 offset:36864
	ds_read_b128 v[200:203], v211 offset:36864
	ds_read_b128 v[204:207], v150 offset:38912
	ds_read_b128 v[208:211], v211 offset:38912
	global_load_lds_dwordx4 v[212:213], off
	v_lshl_add_u64 v[212:213], s[30:31], 0, v[130:131]
	s_mov_b32 m0, s40
	s_nop 0
	global_load_lds_dwordx4 v[212:213], off
	s_waitcnt lgkmcnt(8)
	s_barrier
	s_waitcnt lgkmcnt(0)
	s_setprio 1
	s_waitcnt lgkmcnt(0)
	v_mfma_f32_16x16x32_bf16 v[124:127], v[140:143], v[180:183], v[124:127]
	v_mfma_f32_16x16x32_bf16 v[124:127], v[154:157], v[184:187], v[124:127]
	v_mfma_f32_16x16x32_bf16 v[120:123], v[176:179], v[184:187], v[120:123]
	v_mfma_f32_16x16x32_bf16 v[120:123], v[158:161], v[180:183], v[120:123]
	v_mfma_f32_16x16x32_bf16 v[104:107], v[158:161], v[188:191], v[104:107]
	v_mfma_f32_16x16x32_bf16 v[104:107], v[176:179], v[192:195], v[104:107]
	v_mfma_f32_16x16x32_bf16 v[108:111], v[154:157], v[192:195], v[108:111]
	v_mfma_f32_16x16x32_bf16 v[108:111], v[140:143], v[188:191], v[108:111]
	v_mfma_f32_16x16x32_bf16 v[92:95], v[140:143], v[196:199], v[92:95]
	v_mfma_f32_16x16x32_bf16 v[92:95], v[154:157], v[200:203], v[92:95]
	v_mfma_f32_16x16x32_bf16 v[88:91], v[176:179], v[200:203], v[88:91]
	v_mfma_f32_16x16x32_bf16 v[88:91], v[158:161], v[196:199], v[88:91]
	v_mfma_f32_16x16x32_bf16 v[72:75], v[158:161], v[204:207], v[72:75]
	v_mfma_f32_16x16x32_bf16 v[72:75], v[176:179], v[208:211], v[72:75]
	v_mfma_f32_16x16x32_bf16 v[76:79], v[154:157], v[208:211], v[76:79]
	v_mfma_f32_16x16x32_bf16 v[76:79], v[140:143], v[204:207], v[76:79]
	s_setprio 0
	s_barrier
	s_add_i32 s30, 0, 0x1c000
	s_add_i32 s31, s52, s36
	v_add_u32_e32 v169, s30, v147
	v_lshl_add_u64 v[144:145], v[144:145], 0, s[16:17]
	s_mov_b32 m0, s31
	ds_read_b128 v[212:215], v169
	v_xor_b32_e32 v251, 64, v169
	ds_read_b128 v[240:243], v251
	ds_read_b128 v[244:247], v169 offset:2048
	ds_read_b128 v[248:251], v251 offset:2048
	global_load_lds_dwordx4 v[144:145], off
	v_lshl_add_u64 v[144:145], v[216:217], 0, s[16:17]
	s_add_i32 m0, s31, 0x2000
	s_nop 0
	global_load_lds_dwordx4 v[144:145], off
	s_barrier
	s_waitcnt lgkmcnt(0)
	s_setprio 1
	s_waitcnt lgkmcnt(0)
	v_mfma_f32_16x16x32_bf16 v[116:119], v[212:215], v[180:183], v[116:119]
	v_mfma_f32_16x16x32_bf16 v[116:119], v[240:243], v[184:187], v[116:119]
	v_mfma_f32_16x16x32_bf16 v[112:115], v[248:251], v[184:187], v[112:115]
	v_mfma_f32_16x16x32_bf16 v[112:115], v[244:247], v[180:183], v[112:115]
	v_mfma_f32_16x16x32_bf16 v[96:99], v[244:247], v[188:191], v[96:99]
	v_mfma_f32_16x16x32_bf16 v[96:99], v[248:251], v[192:195], v[96:99]
	v_mfma_f32_16x16x32_bf16 v[100:103], v[240:243], v[192:195], v[100:103]
	v_mfma_f32_16x16x32_bf16 v[100:103], v[212:215], v[188:191], v[100:103]
	v_mfma_f32_16x16x32_bf16 v[84:87], v[212:215], v[196:199], v[84:87]
	v_mfma_f32_16x16x32_bf16 v[84:87], v[240:243], v[200:203], v[84:87]
	v_mfma_f32_16x16x32_bf16 v[80:83], v[248:251], v[200:203], v[80:83]
	v_mfma_f32_16x16x32_bf16 v[80:83], v[244:247], v[196:199], v[80:83]
	v_mfma_f32_16x16x32_bf16 v[64:67], v[244:247], v[204:207], v[64:67]
	v_mfma_f32_16x16x32_bf16 v[64:67], v[248:251], v[208:211], v[64:67]
	v_mfma_f32_16x16x32_bf16 v[68:71], v[240:243], v[208:211], v[68:71]
	v_mfma_f32_16x16x32_bf16 v[68:71], v[212:215], v[204:207], v[68:71]
	s_setprio 0
	s_mov_b32 m0, s42
	v_lshl_add_u64 v[144:145], v[252:253], 0, s[16:17]
	s_barrier
	ds_read_b128 v[180:183], v150 offset:49152
	v_xor_b32_e32 v211, 64, v150
	ds_read_b128 v[184:187], v211 offset:49152
	ds_read_b128 v[188:191], v150 offset:51200
	ds_read_b128 v[192:195], v211 offset:51200
	ds_read_b128 v[196:199], v150 offset:53248
	ds_read_b128 v[200:203], v211 offset:53248
	ds_read_b128 v[204:207], v150 offset:55296
	ds_read_b128 v[208:211], v211 offset:55296
	global_load_lds_dwordx4 v[144:145], off
	v_lshl_add_u64 v[144:145], v[234:235], 0, s[16:17]
	s_mov_b32 m0, s43
	s_nop 0
	global_load_lds_dwordx4 v[144:145], off
	s_barrier
	s_waitcnt lgkmcnt(0)
	s_setprio 1
	s_waitcnt lgkmcnt(0)
	v_mfma_f32_16x16x32_bf16 v[60:63], v[140:143], v[180:183], v[60:63]
	v_mfma_f32_16x16x32_bf16 v[60:63], v[154:157], v[184:187], v[60:63]
	v_mfma_f32_16x16x32_bf16 v[56:59], v[176:179], v[184:187], v[56:59]
	v_mfma_f32_16x16x32_bf16 v[56:59], v[158:161], v[180:183], v[56:59]
	v_mfma_f32_16x16x32_bf16 v[40:43], v[158:161], v[188:191], v[40:43]
	v_mfma_f32_16x16x32_bf16 v[40:43], v[176:179], v[192:195], v[40:43]
	v_mfma_f32_16x16x32_bf16 v[44:47], v[154:157], v[192:195], v[44:47]
	v_mfma_f32_16x16x32_bf16 v[44:47], v[140:143], v[188:191], v[44:47]
	v_mfma_f32_16x16x32_bf16 v[28:31], v[140:143], v[196:199], v[28:31]
	v_mfma_f32_16x16x32_bf16 v[28:31], v[154:157], v[200:203], v[28:31]
	v_mfma_f32_16x16x32_bf16 v[24:27], v[176:179], v[200:203], v[24:27]
	v_mfma_f32_16x16x32_bf16 v[24:27], v[158:161], v[196:199], v[24:27]
	v_mfma_f32_16x16x32_bf16 v[8:11], v[158:161], v[204:207], v[8:11]
	v_mfma_f32_16x16x32_bf16 v[8:11], v[176:179], v[208:211], v[8:11]
	v_mfma_f32_16x16x32_bf16 v[12:15], v[154:157], v[208:211], v[12:15]
	v_mfma_f32_16x16x32_bf16 v[12:15], v[140:143], v[204:207], v[12:15]
	s_setprio 0
	s_barrier
	s_add_u32 s28, s28, 0x80080
	s_addc_u32 s29, s29, 0
	s_add_i32 s30, s30, s36
	v_lshl_add_u64 v[140:141], s[28:29], 0, v[164:165]
	s_mov_b32 m0, s30
	s_nop 0
	global_load_lds_dwordx4 v[140:141], off
	v_lshl_add_u64 v[140:141], s[28:29], 0, v[166:167]
	s_add_i32 m0, s30, 0x2000
	s_nop 0
	global_load_lds_dwordx4 v[140:141], off
	s_waitcnt vmcnt(6)
	s_barrier
	s_setprio 1
	v_mfma_f32_16x16x32_bf16 v[52:55], v[212:215], v[180:183], v[52:55]
	v_mfma_f32_16x16x32_bf16 v[52:55], v[240:243], v[184:187], v[52:55]
	v_mfma_f32_16x16x32_bf16 v[48:51], v[248:251], v[184:187], v[48:51]
	v_mfma_f32_16x16x32_bf16 v[48:51], v[244:247], v[180:183], v[48:51]
	v_mfma_f32_16x16x32_bf16 v[32:35], v[244:247], v[188:191], v[32:35]
	v_mfma_f32_16x16x32_bf16 v[32:35], v[248:251], v[192:195], v[32:35]
	v_mfma_f32_16x16x32_bf16 v[36:39], v[240:243], v[192:195], v[36:39]
	v_mfma_f32_16x16x32_bf16 v[36:39], v[212:215], v[188:191], v[36:39]
	v_mfma_f32_16x16x32_bf16 v[20:23], v[212:215], v[196:199], v[20:23]
	v_mfma_f32_16x16x32_bf16 v[20:23], v[240:243], v[200:203], v[20:23]
	v_mfma_f32_16x16x32_bf16 v[16:19], v[248:251], v[200:203], v[16:19]
	v_mfma_f32_16x16x32_bf16 v[16:19], v[244:247], v[196:199], v[16:19]
	v_mfma_f32_16x16x32_bf16 v[0:3], v[244:247], v[204:207], v[0:3]
	v_mfma_f32_16x16x32_bf16 v[0:3], v[248:251], v[208:211], v[0:3]
	v_mfma_f32_16x16x32_bf16 v[4:7], v[240:243], v[208:211], v[4:7]
	v_mfma_f32_16x16x32_bf16 v[4:7], v[212:215], v[204:207], v[4:7]
	s_setprio 0
	s_add_i32 s49, s49, 2
	s_add_u32 s26, s26, 0x100
	s_addc_u32 s27, s27, 0
	s_add_u32 s33, s33, 0x100
	s_addc_u32 s48, s48, 0
	s_cmp_gt_u32 s49, 29
	s_barrier
	s_cbranch_scc0 .LBB0_599
	v_lshl_add_u32 v143, s12, 8, v146
	v_lshlrev_b32_e32 v145, 2, v143
	global_load_dword v154, v145, s[14:15]
	global_load_dword v155, v145, s[14:15] offset:64
	global_load_dword v156, v145, s[14:15] offset:128
	global_load_dword v157, v145, s[14:15] offset:192
	global_load_dword v158, v145, s[14:15] offset:512
	global_load_dword v159, v145, s[14:15] offset:576
	global_load_dword v160, v145, s[14:15] offset:640
	global_load_dword v161, v145, s[14:15] offset:704
	v_lshlrev_b32_e32 v141, 13, v143
	v_lshl_or_b32 v143, s0, 8, v148
	v_lshl_add_u32 v141, v143, 1, v141
	v_xor_b32_e32 v169, 16, v153
	v_lshlrev_b32_e32 v169, 2, v169
	v_xor_b32_e32 v171, 32, v153
	v_lshlrev_b32_e32 v171, 2, v171
	v_mov_b32_e32 v140, 0xbdd2d3e8
	v_mov_b32_e32 v142, 0xc0135761
	v_mov_b32_e32 v144, 1.0
	s_waitcnt vmcnt(0)
	v_fmamk_f32 v154, v154, 0x3a000000, v152
	v_fmamk_f32 v155, v155, 0x3a000000, v152
	v_fmamk_f32 v156, v156, 0x3a000000, v152
	v_fmamk_f32 v157, v157, 0x3a000000, v152
	v_fmamk_f32 v158, v158, 0x3a000000, v152
	v_fmamk_f32 v159, v159, 0x3a000000, v152
	v_fmamk_f32 v160, v160, 0x3a000000, v152
	v_fmamk_f32 v161, v161, 0x3a000000, v152
	v_rsq_f32_e32 v154, v154
	v_rsq_f32_e32 v155, v155
	v_rsq_f32_e32 v156, v156
	v_rsq_f32_e32 v157, v157
	v_rsq_f32_e32 v158, v158
	v_rsq_f32_e32 v159, v159
	v_rsq_f32_e32 v160, v160
	v_rsq_f32_e32 v161, v161
	v_pk_mul_f32 v[124:125], v[124:125], v[154:155] op_sel:[0,0] op_sel_hi:[1,0]
	v_pk_mul_f32 v[126:127], v[126:127], v[154:155] op_sel:[0,0] op_sel_hi:[1,0]
	v_pk_mul_f32 v[120:121], v[120:121], v[154:155] op_sel:[0,0] op_sel_hi:[1,0]
	v_pk_mul_f32 v[122:123], v[122:123], v[154:155] op_sel:[0,0] op_sel_hi:[1,0]
	v_pk_mul_f32 v[176:177], v[124:125], v[124:125]
	v_pk_mul_f32 v[178:179], v[126:127], v[126:127]
	v_pk_mul_f32 v[180:181], v[120:121], v[120:121]
	v_pk_mul_f32 v[182:183], v[122:123], v[122:123]
	v_pk_fma_f32 v[176:177], v[176:177], v[140:141], v[142:143] op_sel_hi:[1,0,0]
	v_pk_fma_f32 v[178:179], v[178:179], v[140:141], v[142:143] op_sel_hi:[1,0,0]
	v_pk_fma_f32 v[180:181], v[180:181], v[140:141], v[142:143] op_sel_hi:[1,0,0]
	v_pk_fma_f32 v[182:183], v[182:183], v[140:141], v[142:143] op_sel_hi:[1,0,0]
	v_pk_mul_f32 v[176:177], v[124:125], v[176:177]
	v_pk_mul_f32 v[178:179], v[126:127], v[178:179]
	v_pk_mul_f32 v[180:181], v[120:121], v[180:181]
	v_pk_mul_f32 v[182:183], v[122:123], v[182:183]
	v_exp_f32_e32 v176, v176
	v_exp_f32_e32 v177, v177
	v_exp_f32_e32 v178, v178
	v_exp_f32_e32 v179, v179
	v_exp_f32_e32 v180, v180
	v_exp_f32_e32 v181, v181
	v_exp_f32_e32 v182, v182
	v_exp_f32_e32 v183, v183
	v_pk_add_f32 v[176:177], v[176:177], v[144:145] op_sel_hi:[1,0]
	v_pk_add_f32 v[178:179], v[178:179], v[144:145] op_sel_hi:[1,0]
	v_pk_add_f32 v[180:181], v[180:181], v[144:145] op_sel_hi:[1,0]
	v_pk_add_f32 v[182:183], v[182:183], v[144:145] op_sel_hi:[1,0]
	v_rcp_f32_e32 v176, v176
	v_rcp_f32_e32 v177, v177
	v_rcp_f32_e32 v178, v178
	v_rcp_f32_e32 v179, v179
	v_rcp_f32_e32 v180, v180
	v_rcp_f32_e32 v181, v181
	v_rcp_f32_e32 v182, v182
	v_rcp_f32_e32 v183, v183
	v_pk_mul_f32 v[124:125], v[124:125], v[176:177]
	v_pk_mul_f32 v[126:127], v[126:127], v[178:179]
	v_pk_mul_f32 v[120:121], v[120:121], v[180:181]
	v_pk_mul_f32 v[122:123], v[122:123], v[182:183]
	v_pk_mul_f32 v[184:185], v[124:125], v[124:125]
	v_pk_fma_f32 v[184:185], v[126:127], v[126:127], v[184:185]
	v_pk_fma_f32 v[184:185], v[120:121], v[120:121], v[184:185]
	v_pk_fma_f32 v[184:185], v[122:123], v[122:123], v[184:185]
	v_cvt_pk_bf16_f32 v124, v124, v125
	v_cvt_pk_bf16_f32 v125, v126, v127
	v_cvt_pk_bf16_f32 v126, v120, v121
	v_cvt_pk_bf16_f32 v127, v122, v123
	global_store_dwordx4 v141, v[124:127], s[96:97]
	v_pk_mul_f32 v[116:117], v[116:117], v[154:155] op_sel:[0,0] op_sel_hi:[1,0]
	v_pk_mul_f32 v[118:119], v[118:119], v[154:155] op_sel:[0,0] op_sel_hi:[1,0]
	v_pk_mul_f32 v[112:113], v[112:113], v[154:155] op_sel:[0,0] op_sel_hi:[1,0]
	v_pk_mul_f32 v[114:115], v[114:115], v[154:155] op_sel:[0,0] op_sel_hi:[1,0]
	v_pk_mul_f32 v[176:177], v[116:117], v[116:117]
	v_pk_mul_f32 v[178:179], v[118:119], v[118:119]
	v_pk_mul_f32 v[180:181], v[112:113], v[112:113]
	v_pk_mul_f32 v[182:183], v[114:115], v[114:115]
	v_pk_fma_f32 v[176:177], v[176:177], v[140:141], v[142:143] op_sel_hi:[1,0,0]
	v_pk_fma_f32 v[178:179], v[178:179], v[140:141], v[142:143] op_sel_hi:[1,0,0]
	v_pk_fma_f32 v[180:181], v[180:181], v[140:141], v[142:143] op_sel_hi:[1,0,0]
	v_pk_fma_f32 v[182:183], v[182:183], v[140:141], v[142:143] op_sel_hi:[1,0,0]
	v_pk_mul_f32 v[176:177], v[116:117], v[176:177]
	v_pk_mul_f32 v[178:179], v[118:119], v[178:179]
	v_pk_mul_f32 v[180:181], v[112:113], v[180:181]
	v_pk_mul_f32 v[182:183], v[114:115], v[182:183]
	v_exp_f32_e32 v176, v176
	v_exp_f32_e32 v177, v177
	v_exp_f32_e32 v178, v178
	v_exp_f32_e32 v179, v179
	v_exp_f32_e32 v180, v180
	v_exp_f32_e32 v181, v181
	v_exp_f32_e32 v182, v182
	v_exp_f32_e32 v183, v183
	v_pk_add_f32 v[176:177], v[176:177], v[144:145] op_sel_hi:[1,0]
	v_pk_add_f32 v[178:179], v[178:179], v[144:145] op_sel_hi:[1,0]
	v_pk_add_f32 v[180:181], v[180:181], v[144:145] op_sel_hi:[1,0]
	v_pk_add_f32 v[182:183], v[182:183], v[144:145] op_sel_hi:[1,0]
	v_rcp_f32_e32 v176, v176
	v_rcp_f32_e32 v177, v177
	v_rcp_f32_e32 v178, v178
	v_rcp_f32_e32 v179, v179
	v_rcp_f32_e32 v180, v180
	v_rcp_f32_e32 v181, v181
	v_rcp_f32_e32 v182, v182
	v_rcp_f32_e32 v183, v183
	v_pk_mul_f32 v[116:117], v[116:117], v[176:177]
	v_pk_mul_f32 v[118:119], v[118:119], v[178:179]
	v_pk_mul_f32 v[112:113], v[112:113], v[180:181]
	v_pk_mul_f32 v[114:115], v[114:115], v[182:183]
	v_pk_fma_f32 v[184:185], v[116:117], v[116:117], v[184:185]
	v_pk_fma_f32 v[184:185], v[118:119], v[118:119], v[184:185]
	v_pk_fma_f32 v[184:185], v[112:113], v[112:113], v[184:185]
	v_pk_fma_f32 v[184:185], v[114:115], v[114:115], v[184:185]
	v_cvt_pk_bf16_f32 v116, v116, v117
	v_cvt_pk_bf16_f32 v117, v118, v119
	v_cvt_pk_bf16_f32 v118, v112, v113
	v_cvt_pk_bf16_f32 v119, v114, v115
	global_store_dwordx4 v141, v[116:119], s[96:97] offset:256
	s_cmp_lt_i32 s0, 8
	s_cbranch_scc1 .Le2_skip0
	v_add_f32_e32 v184, v184, v185
	ds_bpermute_b32 v173, v169, v184
	s_waitcnt lgkmcnt(0)
	v_add_f32_e32 v184, v184, v173
	ds_bpermute_b32 v173, v171, v184
	s_waitcnt lgkmcnt(0)
	v_add_f32_e32 v184, v184, v173
	s_mov_b64 exec, s[8:9]
	global_atomic_add_f32 v145, v184, s[4:5]
	s_mov_b64 exec, -1
.Le2_skip0:
	v_pk_mul_f32 v[108:109], v[108:109], v[154:155] op_sel:[0,1] op_sel_hi:[1,1]
	v_pk_mul_f32 v[110:111], v[110:111], v[154:155] op_sel:[0,1] op_sel_hi:[1,1]
	v_pk_mul_f32 v[104:105], v[104:105], v[154:155] op_sel:[0,1] op_sel_hi:[1,1]
	v_pk_mul_f32 v[106:107], v[106:107], v[154:155] op_sel:[0,1] op_sel_hi:[1,1]
	v_pk_mul_f32 v[176:177], v[108:109], v[108:109]
	v_pk_mul_f32 v[178:179], v[110:111], v[110:111]
	v_pk_mul_f32 v[180:181], v[104:105], v[104:105]
	v_pk_mul_f32 v[182:183], v[106:107], v[106:107]
	v_pk_fma_f32 v[176:177], v[176:177], v[140:141], v[142:143] op_sel_hi:[1,0,0]
	v_pk_fma_f32 v[178:179], v[178:179], v[140:141], v[142:143] op_sel_hi:[1,0,0]
	v_pk_fma_f32 v[180:181], v[180:181], v[140:141], v[142:143] op_sel_hi:[1,0,0]
	v_pk_fma_f32 v[182:183], v[182:183], v[140:141], v[142:143] op_sel_hi:[1,0,0]
	v_pk_mul_f32 v[176:177], v[108:109], v[176:177]
	v_pk_mul_f32 v[178:179], v[110:111], v[178:179]
	v_pk_mul_f32 v[180:181], v[104:105], v[180:181]
	v_pk_mul_f32 v[182:183], v[106:107], v[182:183]
	v_exp_f32_e32 v176, v176
	v_exp_f32_e32 v177, v177
	v_exp_f32_e32 v178, v178
	v_exp_f32_e32 v179, v179
	v_exp_f32_e32 v180, v180
	v_exp_f32_e32 v181, v181
	v_exp_f32_e32 v182, v182
	v_exp_f32_e32 v183, v183
	v_pk_add_f32 v[176:177], v[176:177], v[144:145] op_sel_hi:[1,0]
	v_pk_add_f32 v[178:179], v[178:179], v[144:145] op_sel_hi:[1,0]
	v_pk_add_f32 v[180:181], v[180:181], v[144:145] op_sel_hi:[1,0]
	v_pk_add_f32 v[182:183], v[182:183], v[144:145] op_sel_hi:[1,0]
	v_rcp_f32_e32 v176, v176
	v_rcp_f32_e32 v177, v177
	v_rcp_f32_e32 v178, v178
	v_rcp_f32_e32 v179, v179
	v_rcp_f32_e32 v180, v180
	v_rcp_f32_e32 v181, v181
	v_rcp_f32_e32 v182, v182
	v_rcp_f32_e32 v183, v183
	v_pk_mul_f32 v[108:109], v[108:109], v[176:177]
	v_pk_mul_f32 v[110:111], v[110:111], v[178:179]
	v_pk_mul_f32 v[104:105], v[104:105], v[180:181]
	v_pk_mul_f32 v[106:107], v[106:107], v[182:183]
	v_pk_mul_f32 v[184:185], v[108:109], v[108:109]
	v_pk_fma_f32 v[184:185], v[110:111], v[110:111], v[184:185]
	v_pk_fma_f32 v[184:185], v[104:105], v[104:105], v[184:185]
	v_pk_fma_f32 v[184:185], v[106:107], v[106:107], v[184:185]
	v_cvt_pk_bf16_f32 v108, v108, v109
	v_cvt_pk_bf16_f32 v109, v110, v111
	v_cvt_pk_bf16_f32 v110, v104, v105
	v_cvt_pk_bf16_f32 v111, v106, v107
	v_add_u32_e32 v143, 0x20000, v141
	global_store_dwordx4 v143, v[108:111], s[96:97]
	v_pk_mul_f32 v[100:101], v[100:101], v[154:155] op_sel:[0,1] op_sel_hi:[1,1]
	v_pk_mul_f32 v[102:103], v[102:103], v[154:155] op_sel:[0,1] op_sel_hi:[1,1]
	v_pk_mul_f32 v[96:97], v[96:97], v[154:155] op_sel:[0,1] op_sel_hi:[1,1]
	v_pk_mul_f32 v[98:99], v[98:99], v[154:155] op_sel:[0,1] op_sel_hi:[1,1]
	v_pk_mul_f32 v[176:177], v[100:101], v[100:101]
	v_pk_mul_f32 v[178:179], v[102:103], v[102:103]
	v_pk_mul_f32 v[180:181], v[96:97], v[96:97]
	v_pk_mul_f32 v[182:183], v[98:99], v[98:99]
	v_pk_fma_f32 v[176:177], v[176:177], v[140:141], v[142:143] op_sel_hi:[1,0,0]
	v_pk_fma_f32 v[178:179], v[178:179], v[140:141], v[142:143] op_sel_hi:[1,0,0]
	v_pk_fma_f32 v[180:181], v[180:181], v[140:141], v[142:143] op_sel_hi:[1,0,0]
	v_pk_fma_f32 v[182:183], v[182:183], v[140:141], v[142:143] op_sel_hi:[1,0,0]
	v_pk_mul_f32 v[176:177], v[100:101], v[176:177]
	v_pk_mul_f32 v[178:179], v[102:103], v[178:179]
	v_pk_mul_f32 v[180:181], v[96:97], v[180:181]
	v_pk_mul_f32 v[182:183], v[98:99], v[182:183]
	v_exp_f32_e32 v176, v176
	v_exp_f32_e32 v177, v177
	v_exp_f32_e32 v178, v178
	v_exp_f32_e32 v179, v179
	v_exp_f32_e32 v180, v180
	v_exp_f32_e32 v181, v181
	v_exp_f32_e32 v182, v182
	v_exp_f32_e32 v183, v183
	v_pk_add_f32 v[176:177], v[176:177], v[144:145] op_sel_hi:[1,0]
	v_pk_add_f32 v[178:179], v[178:179], v[144:145] op_sel_hi:[1,0]
	v_pk_add_f32 v[180:181], v[180:181], v[144:145] op_sel_hi:[1,0]
	v_pk_add_f32 v[182:183], v[182:183], v[144:145] op_sel_hi:[1,0]
	v_rcp_f32_e32 v176, v176
	v_rcp_f32_e32 v177, v177
	v_rcp_f32_e32 v178, v178
	v_rcp_f32_e32 v179, v179
	v_rcp_f32_e32 v180, v180
	v_rcp_f32_e32 v181, v181
	v_rcp_f32_e32 v182, v182
	v_rcp_f32_e32 v183, v183
	v_pk_mul_f32 v[100:101], v[100:101], v[176:177]
	v_pk_mul_f32 v[102:103], v[102:103], v[178:179]
	v_pk_mul_f32 v[96:97], v[96:97], v[180:181]
	v_pk_mul_f32 v[98:99], v[98:99], v[182:183]
	v_pk_fma_f32 v[184:185], v[100:101], v[100:101], v[184:185]
	v_pk_fma_f32 v[184:185], v[102:103], v[102:103], v[184:185]
	v_pk_fma_f32 v[184:185], v[96:97], v[96:97], v[184:185]
	v_pk_fma_f32 v[184:185], v[98:99], v[98:99], v[184:185]
	v_cvt_pk_bf16_f32 v100, v100, v101
	v_cvt_pk_bf16_f32 v101, v102, v103
	v_cvt_pk_bf16_f32 v102, v96, v97
	v_cvt_pk_bf16_f32 v103, v98, v99
	global_store_dwordx4 v143, v[100:103], s[96:97] offset:256
	s_cmp_lt_i32 s0, 8
	s_cbranch_scc1 .Le2_skip1
	v_add_f32_e32 v184, v184, v185
	ds_bpermute_b32 v173, v169, v184
	s_waitcnt lgkmcnt(0)
	v_add_f32_e32 v184, v184, v173
	ds_bpermute_b32 v173, v171, v184
	s_waitcnt lgkmcnt(0)
	v_add_f32_e32 v184, v184, v173
	s_mov_b64 exec, s[8:9]
	global_atomic_add_f32 v145, v184, s[4:5] offset:64
	s_mov_b64 exec, -1
.Le2_skip1:
	v_pk_mul_f32 v[92:93], v[92:93], v[156:157] op_sel:[0,0] op_sel_hi:[1,0]
	v_pk_mul_f32 v[94:95], v[94:95], v[156:157] op_sel:[0,0] op_sel_hi:[1,0]
	v_pk_mul_f32 v[88:89], v[88:89], v[156:157] op_sel:[0,0] op_sel_hi:[1,0]
	v_pk_mul_f32 v[90:91], v[90:91], v[156:157] op_sel:[0,0] op_sel_hi:[1,0]
	v_pk_mul_f32 v[176:177], v[92:93], v[92:93]
	v_pk_mul_f32 v[178:179], v[94:95], v[94:95]
	v_pk_mul_f32 v[180:181], v[88:89], v[88:89]
	v_pk_mul_f32 v[182:183], v[90:91], v[90:91]
	v_pk_fma_f32 v[176:177], v[176:177], v[140:141], v[142:143] op_sel_hi:[1,0,0]
	v_pk_fma_f32 v[178:179], v[178:179], v[140:141], v[142:143] op_sel_hi:[1,0,0]
	v_pk_fma_f32 v[180:181], v[180:181], v[140:141], v[142:143] op_sel_hi:[1,0,0]
	v_pk_fma_f32 v[182:183], v[182:183], v[140:141], v[142:143] op_sel_hi:[1,0,0]
	v_pk_mul_f32 v[176:177], v[92:93], v[176:177]
	v_pk_mul_f32 v[178:179], v[94:95], v[178:179]
	v_pk_mul_f32 v[180:181], v[88:89], v[180:181]
	v_pk_mul_f32 v[182:183], v[90:91], v[182:183]
	v_exp_f32_e32 v176, v176
	v_exp_f32_e32 v177, v177
	v_exp_f32_e32 v178, v178
	v_exp_f32_e32 v179, v179
	v_exp_f32_e32 v180, v180
	v_exp_f32_e32 v181, v181
	v_exp_f32_e32 v182, v182
	v_exp_f32_e32 v183, v183
	v_pk_add_f32 v[176:177], v[176:177], v[144:145] op_sel_hi:[1,0]
	v_pk_add_f32 v[178:179], v[178:179], v[144:145] op_sel_hi:[1,0]
	v_pk_add_f32 v[180:181], v[180:181], v[144:145] op_sel_hi:[1,0]
	v_pk_add_f32 v[182:183], v[182:183], v[144:145] op_sel_hi:[1,0]
	v_rcp_f32_e32 v176, v176
	v_rcp_f32_e32 v177, v177
	v_rcp_f32_e32 v178, v178
	v_rcp_f32_e32 v179, v179
	v_rcp_f32_e32 v180, v180
	v_rcp_f32_e32 v181, v181
	v_rcp_f32_e32 v182, v182
	v_rcp_f32_e32 v183, v183
	v_pk_mul_f32 v[92:93], v[92:93], v[176:177]
	v_pk_mul_f32 v[94:95], v[94:95], v[178:179]
	v_pk_mul_f32 v[88:89], v[88:89], v[180:181]
	v_pk_mul_f32 v[90:91], v[90:91], v[182:183]
	v_pk_mul_f32 v[184:185], v[92:93], v[92:93]
	v_pk_fma_f32 v[184:185], v[94:95], v[94:95], v[184:185]
	v_pk_fma_f32 v[184:185], v[88:89], v[88:89], v[184:185]
	v_pk_fma_f32 v[184:185], v[90:91], v[90:91], v[184:185]
	v_cvt_pk_bf16_f32 v92, v92, v93
	v_cvt_pk_bf16_f32 v93, v94, v95
	v_cvt_pk_bf16_f32 v94, v88, v89
	v_cvt_pk_bf16_f32 v95, v90, v91
	v_add_u32_e32 v143, 0x40000, v141
	global_store_dwordx4 v143, v[92:95], s[96:97]
	v_pk_mul_f32 v[84:85], v[84:85], v[156:157] op_sel:[0,0] op_sel_hi:[1,0]
	v_pk_mul_f32 v[86:87], v[86:87], v[156:157] op_sel:[0,0] op_sel_hi:[1,0]
	v_pk_mul_f32 v[80:81], v[80:81], v[156:157] op_sel:[0,0] op_sel_hi:[1,0]
	v_pk_mul_f32 v[82:83], v[82:83], v[156:157] op_sel:[0,0] op_sel_hi:[1,0]
	v_pk_mul_f32 v[176:177], v[84:85], v[84:85]
	v_pk_mul_f32 v[178:179], v[86:87], v[86:87]
	v_pk_mul_f32 v[180:181], v[80:81], v[80:81]
	v_pk_mul_f32 v[182:183], v[82:83], v[82:83]
	v_pk_fma_f32 v[176:177], v[176:177], v[140:141], v[142:143] op_sel_hi:[1,0,0]
	v_pk_fma_f32 v[178:179], v[178:179], v[140:141], v[142:143] op_sel_hi:[1,0,0]
	v_pk_fma_f32 v[180:181], v[180:181], v[140:141], v[142:143] op_sel_hi:[1,0,0]
	v_pk_fma_f32 v[182:183], v[182:183], v[140:141], v[142:143] op_sel_hi:[1,0,0]
	v_pk_mul_f32 v[176:177], v[84:85], v[176:177]
	v_pk_mul_f32 v[178:179], v[86:87], v[178:179]
	v_pk_mul_f32 v[180:181], v[80:81], v[180:181]
	v_pk_mul_f32 v[182:183], v[82:83], v[182:183]
	v_exp_f32_e32 v176, v176
	v_exp_f32_e32 v177, v177
	v_exp_f32_e32 v178, v178
	v_exp_f32_e32 v179, v179
	v_exp_f32_e32 v180, v180
	v_exp_f32_e32 v181, v181
	v_exp_f32_e32 v182, v182
	v_exp_f32_e32 v183, v183
	v_pk_add_f32 v[176:177], v[176:177], v[144:145] op_sel_hi:[1,0]
	v_pk_add_f32 v[178:179], v[178:179], v[144:145] op_sel_hi:[1,0]
	v_pk_add_f32 v[180:181], v[180:181], v[144:145] op_sel_hi:[1,0]
	v_pk_add_f32 v[182:183], v[182:183], v[144:145] op_sel_hi:[1,0]
	v_rcp_f32_e32 v176, v176
	v_rcp_f32_e32 v177, v177
	v_rcp_f32_e32 v178, v178
	v_rcp_f32_e32 v179, v179
	v_rcp_f32_e32 v180, v180
	v_rcp_f32_e32 v181, v181
	v_rcp_f32_e32 v182, v182
	v_rcp_f32_e32 v183, v183
	v_pk_mul_f32 v[84:85], v[84:85], v[176:177]
	v_pk_mul_f32 v[86:87], v[86:87], v[178:179]
	v_pk_mul_f32 v[80:81], v[80:81], v[180:181]
	v_pk_mul_f32 v[82:83], v[82:83], v[182:183]
	v_pk_fma_f32 v[184:185], v[84:85], v[84:85], v[184:185]
	v_pk_fma_f32 v[184:185], v[86:87], v[86:87], v[184:185]
	v_pk_fma_f32 v[184:185], v[80:81], v[80:81], v[184:185]
	v_pk_fma_f32 v[184:185], v[82:83], v[82:83], v[184:185]
	v_cvt_pk_bf16_f32 v84, v84, v85
	v_cvt_pk_bf16_f32 v85, v86, v87
	v_cvt_pk_bf16_f32 v86, v80, v81
	v_cvt_pk_bf16_f32 v87, v82, v83
	global_store_dwordx4 v143, v[84:87], s[96:97] offset:256
	s_cmp_lt_i32 s0, 8
	s_cbranch_scc1 .Le2_skip2
	v_add_f32_e32 v184, v184, v185
	ds_bpermute_b32 v173, v169, v184
	s_waitcnt lgkmcnt(0)
	v_add_f32_e32 v184, v184, v173
	ds_bpermute_b32 v173, v171, v184
	s_waitcnt lgkmcnt(0)
	v_add_f32_e32 v184, v184, v173
	s_mov_b64 exec, s[8:9]
	global_atomic_add_f32 v145, v184, s[4:5] offset:128
	s_mov_b64 exec, -1
.Le2_skip2:
	v_pk_mul_f32 v[76:77], v[76:77], v[156:157] op_sel:[0,1] op_sel_hi:[1,1]
	v_pk_mul_f32 v[78:79], v[78:79], v[156:157] op_sel:[0,1] op_sel_hi:[1,1]
	v_pk_mul_f32 v[72:73], v[72:73], v[156:157] op_sel:[0,1] op_sel_hi:[1,1]
	v_pk_mul_f32 v[74:75], v[74:75], v[156:157] op_sel:[0,1] op_sel_hi:[1,1]
	v_pk_mul_f32 v[176:177], v[76:77], v[76:77]
	v_pk_mul_f32 v[178:179], v[78:79], v[78:79]
	v_pk_mul_f32 v[180:181], v[72:73], v[72:73]
	v_pk_mul_f32 v[182:183], v[74:75], v[74:75]
	v_pk_fma_f32 v[176:177], v[176:177], v[140:141], v[142:143] op_sel_hi:[1,0,0]
	v_pk_fma_f32 v[178:179], v[178:179], v[140:141], v[142:143] op_sel_hi:[1,0,0]
	v_pk_fma_f32 v[180:181], v[180:181], v[140:141], v[142:143] op_sel_hi:[1,0,0]
	v_pk_fma_f32 v[182:183], v[182:183], v[140:141], v[142:143] op_sel_hi:[1,0,0]
	v_pk_mul_f32 v[176:177], v[76:77], v[176:177]
	v_pk_mul_f32 v[178:179], v[78:79], v[178:179]
	v_pk_mul_f32 v[180:181], v[72:73], v[180:181]
	v_pk_mul_f32 v[182:183], v[74:75], v[182:183]
	v_exp_f32_e32 v176, v176
	v_exp_f32_e32 v177, v177
	v_exp_f32_e32 v178, v178
	v_exp_f32_e32 v179, v179
	v_exp_f32_e32 v180, v180
	v_exp_f32_e32 v181, v181
	v_exp_f32_e32 v182, v182
	v_exp_f32_e32 v183, v183
	v_pk_add_f32 v[176:177], v[176:177], v[144:145] op_sel_hi:[1,0]
	v_pk_add_f32 v[178:179], v[178:179], v[144:145] op_sel_hi:[1,0]
	v_pk_add_f32 v[180:181], v[180:181], v[144:145] op_sel_hi:[1,0]
	v_pk_add_f32 v[182:183], v[182:183], v[144:145] op_sel_hi:[1,0]
	v_rcp_f32_e32 v176, v176
	v_rcp_f32_e32 v177, v177
	v_rcp_f32_e32 v178, v178
	v_rcp_f32_e32 v179, v179
	v_rcp_f32_e32 v180, v180
	v_rcp_f32_e32 v181, v181
	v_rcp_f32_e32 v182, v182
	v_rcp_f32_e32 v183, v183
	v_pk_mul_f32 v[76:77], v[76:77], v[176:177]
	v_pk_mul_f32 v[78:79], v[78:79], v[178:179]
	v_pk_mul_f32 v[72:73], v[72:73], v[180:181]
	v_pk_mul_f32 v[74:75], v[74:75], v[182:183]
	v_pk_mul_f32 v[184:185], v[76:77], v[76:77]
	v_pk_fma_f32 v[184:185], v[78:79], v[78:79], v[184:185]
	v_pk_fma_f32 v[184:185], v[72:73], v[72:73], v[184:185]
	v_pk_fma_f32 v[184:185], v[74:75], v[74:75], v[184:185]
	v_cvt_pk_bf16_f32 v76, v76, v77
	v_cvt_pk_bf16_f32 v77, v78, v79
	v_cvt_pk_bf16_f32 v78, v72, v73
	v_cvt_pk_bf16_f32 v79, v74, v75
	v_add_u32_e32 v143, 0x60000, v141
	global_store_dwordx4 v143, v[76:79], s[96:97]
	v_pk_mul_f32 v[68:69], v[68:69], v[156:157] op_sel:[0,1] op_sel_hi:[1,1]
	v_pk_mul_f32 v[70:71], v[70:71], v[156:157] op_sel:[0,1] op_sel_hi:[1,1]
	v_pk_mul_f32 v[64:65], v[64:65], v[156:157] op_sel:[0,1] op_sel_hi:[1,1]
	v_pk_mul_f32 v[66:67], v[66:67], v[156:157] op_sel:[0,1] op_sel_hi:[1,1]
	v_pk_mul_f32 v[176:177], v[68:69], v[68:69]
	v_pk_mul_f32 v[178:179], v[70:71], v[70:71]
	v_pk_mul_f32 v[180:181], v[64:65], v[64:65]
	v_pk_mul_f32 v[182:183], v[66:67], v[66:67]
	v_pk_fma_f32 v[176:177], v[176:177], v[140:141], v[142:143] op_sel_hi:[1,0,0]
	v_pk_fma_f32 v[178:179], v[178:179], v[140:141], v[142:143] op_sel_hi:[1,0,0]
	v_pk_fma_f32 v[180:181], v[180:181], v[140:141], v[142:143] op_sel_hi:[1,0,0]
	v_pk_fma_f32 v[182:183], v[182:183], v[140:141], v[142:143] op_sel_hi:[1,0,0]
	v_pk_mul_f32 v[176:177], v[68:69], v[176:177]
	v_pk_mul_f32 v[178:179], v[70:71], v[178:179]
	v_pk_mul_f32 v[180:181], v[64:65], v[180:181]
	v_pk_mul_f32 v[182:183], v[66:67], v[182:183]
	v_exp_f32_e32 v176, v176
	v_exp_f32_e32 v177, v177
	v_exp_f32_e32 v178, v178
	v_exp_f32_e32 v179, v179
	v_exp_f32_e32 v180, v180
	v_exp_f32_e32 v181, v181
	v_exp_f32_e32 v182, v182
	v_exp_f32_e32 v183, v183
	v_pk_add_f32 v[176:177], v[176:177], v[144:145] op_sel_hi:[1,0]
	v_pk_add_f32 v[178:179], v[178:179], v[144:145] op_sel_hi:[1,0]
	v_pk_add_f32 v[180:181], v[180:181], v[144:145] op_sel_hi:[1,0]
	v_pk_add_f32 v[182:183], v[182:183], v[144:145] op_sel_hi:[1,0]
	v_rcp_f32_e32 v176, v176
	v_rcp_f32_e32 v177, v177
	v_rcp_f32_e32 v178, v178
	v_rcp_f32_e32 v179, v179
	v_rcp_f32_e32 v180, v180
	v_rcp_f32_e32 v181, v181
	v_rcp_f32_e32 v182, v182
	v_rcp_f32_e32 v183, v183
	v_pk_mul_f32 v[68:69], v[68:69], v[176:177]
	v_pk_mul_f32 v[70:71], v[70:71], v[178:179]
	v_pk_mul_f32 v[64:65], v[64:65], v[180:181]
	v_pk_mul_f32 v[66:67], v[66:67], v[182:183]
	v_pk_fma_f32 v[184:185], v[68:69], v[68:69], v[184:185]
	v_pk_fma_f32 v[184:185], v[70:71], v[70:71], v[184:185]
	v_pk_fma_f32 v[184:185], v[64:65], v[64:65], v[184:185]
	v_pk_fma_f32 v[184:185], v[66:67], v[66:67], v[184:185]
	v_cvt_pk_bf16_f32 v68, v68, v69
	v_cvt_pk_bf16_f32 v69, v70, v71
	v_cvt_pk_bf16_f32 v70, v64, v65
	v_cvt_pk_bf16_f32 v71, v66, v67
	global_store_dwordx4 v143, v[68:71], s[96:97] offset:256
	s_cmp_lt_i32 s0, 8
	s_cbranch_scc1 .Le2_skip3
	v_add_f32_e32 v184, v184, v185
	ds_bpermute_b32 v173, v169, v184
	s_waitcnt lgkmcnt(0)
	v_add_f32_e32 v184, v184, v173
	ds_bpermute_b32 v173, v171, v184
	s_waitcnt lgkmcnt(0)
	v_add_f32_e32 v184, v184, v173
	s_mov_b64 exec, s[8:9]
	global_atomic_add_f32 v145, v184, s[4:5] offset:192
	s_mov_b64 exec, -1
.Le2_skip3:
	v_pk_mul_f32 v[60:61], v[60:61], v[158:159] op_sel:[0,0] op_sel_hi:[1,0]
	v_pk_mul_f32 v[62:63], v[62:63], v[158:159] op_sel:[0,0] op_sel_hi:[1,0]
	v_pk_mul_f32 v[56:57], v[56:57], v[158:159] op_sel:[0,0] op_sel_hi:[1,0]
	v_pk_mul_f32 v[58:59], v[58:59], v[158:159] op_sel:[0,0] op_sel_hi:[1,0]
	v_pk_mul_f32 v[176:177], v[60:61], v[60:61]
	v_pk_mul_f32 v[178:179], v[62:63], v[62:63]
	v_pk_mul_f32 v[180:181], v[56:57], v[56:57]
	v_pk_mul_f32 v[182:183], v[58:59], v[58:59]
	v_pk_fma_f32 v[176:177], v[176:177], v[140:141], v[142:143] op_sel_hi:[1,0,0]
	v_pk_fma_f32 v[178:179], v[178:179], v[140:141], v[142:143] op_sel_hi:[1,0,0]
	v_pk_fma_f32 v[180:181], v[180:181], v[140:141], v[142:143] op_sel_hi:[1,0,0]
	v_pk_fma_f32 v[182:183], v[182:183], v[140:141], v[142:143] op_sel_hi:[1,0,0]
	v_pk_mul_f32 v[176:177], v[60:61], v[176:177]
	v_pk_mul_f32 v[178:179], v[62:63], v[178:179]
	v_pk_mul_f32 v[180:181], v[56:57], v[180:181]
	v_pk_mul_f32 v[182:183], v[58:59], v[182:183]
	v_exp_f32_e32 v176, v176
	v_exp_f32_e32 v177, v177
	v_exp_f32_e32 v178, v178
	v_exp_f32_e32 v179, v179
	v_exp_f32_e32 v180, v180
	v_exp_f32_e32 v181, v181
	v_exp_f32_e32 v182, v182
	v_exp_f32_e32 v183, v183
	v_pk_add_f32 v[176:177], v[176:177], v[144:145] op_sel_hi:[1,0]
	v_pk_add_f32 v[178:179], v[178:179], v[144:145] op_sel_hi:[1,0]
	v_pk_add_f32 v[180:181], v[180:181], v[144:145] op_sel_hi:[1,0]
	v_pk_add_f32 v[182:183], v[182:183], v[144:145] op_sel_hi:[1,0]
	v_rcp_f32_e32 v176, v176
	v_rcp_f32_e32 v177, v177
	v_rcp_f32_e32 v178, v178
	v_rcp_f32_e32 v179, v179
	v_rcp_f32_e32 v180, v180
	v_rcp_f32_e32 v181, v181
	v_rcp_f32_e32 v182, v182
	v_rcp_f32_e32 v183, v183
	v_pk_mul_f32 v[60:61], v[60:61], v[176:177]
	v_pk_mul_f32 v[62:63], v[62:63], v[178:179]
	v_pk_mul_f32 v[56:57], v[56:57], v[180:181]
	v_pk_mul_f32 v[58:59], v[58:59], v[182:183]
	v_pk_mul_f32 v[184:185], v[60:61], v[60:61]
	v_pk_fma_f32 v[184:185], v[62:63], v[62:63], v[184:185]
	v_pk_fma_f32 v[184:185], v[56:57], v[56:57], v[184:185]
	v_pk_fma_f32 v[184:185], v[58:59], v[58:59], v[184:185]
	v_cvt_pk_bf16_f32 v60, v60, v61
	v_cvt_pk_bf16_f32 v61, v62, v63
	v_cvt_pk_bf16_f32 v62, v56, v57
	v_cvt_pk_bf16_f32 v63, v58, v59
	v_add_u32_e32 v143, 0x100000, v141
	global_store_dwordx4 v143, v[60:63], s[96:97]
	v_pk_mul_f32 v[52:53], v[52:53], v[158:159] op_sel:[0,0] op_sel_hi:[1,0]
	v_pk_mul_f32 v[54:55], v[54:55], v[158:159] op_sel:[0,0] op_sel_hi:[1,0]
	v_pk_mul_f32 v[48:49], v[48:49], v[158:159] op_sel:[0,0] op_sel_hi:[1,0]
	v_pk_mul_f32 v[50:51], v[50:51], v[158:159] op_sel:[0,0] op_sel_hi:[1,0]
	v_pk_mul_f32 v[176:177], v[52:53], v[52:53]
	v_pk_mul_f32 v[178:179], v[54:55], v[54:55]
	v_pk_mul_f32 v[180:181], v[48:49], v[48:49]
	v_pk_mul_f32 v[182:183], v[50:51], v[50:51]
	v_pk_fma_f32 v[176:177], v[176:177], v[140:141], v[142:143] op_sel_hi:[1,0,0]
	v_pk_fma_f32 v[178:179], v[178:179], v[140:141], v[142:143] op_sel_hi:[1,0,0]
	v_pk_fma_f32 v[180:181], v[180:181], v[140:141], v[142:143] op_sel_hi:[1,0,0]
	v_pk_fma_f32 v[182:183], v[182:183], v[140:141], v[142:143] op_sel_hi:[1,0,0]
	v_pk_mul_f32 v[176:177], v[52:53], v[176:177]
	v_pk_mul_f32 v[178:179], v[54:55], v[178:179]
	v_pk_mul_f32 v[180:181], v[48:49], v[180:181]
	v_pk_mul_f32 v[182:183], v[50:51], v[182:183]
	v_exp_f32_e32 v176, v176
	v_exp_f32_e32 v177, v177
	v_exp_f32_e32 v178, v178
	v_exp_f32_e32 v179, v179
	v_exp_f32_e32 v180, v180
	v_exp_f32_e32 v181, v181
	v_exp_f32_e32 v182, v182
	v_exp_f32_e32 v183, v183
	v_pk_add_f32 v[176:177], v[176:177], v[144:145] op_sel_hi:[1,0]
	v_pk_add_f32 v[178:179], v[178:179], v[144:145] op_sel_hi:[1,0]
	v_pk_add_f32 v[180:181], v[180:181], v[144:145] op_sel_hi:[1,0]
	v_pk_add_f32 v[182:183], v[182:183], v[144:145] op_sel_hi:[1,0]
	v_rcp_f32_e32 v176, v176
	v_rcp_f32_e32 v177, v177
	v_rcp_f32_e32 v178, v178
	v_rcp_f32_e32 v179, v179
	v_rcp_f32_e32 v180, v180
	v_rcp_f32_e32 v181, v181
	v_rcp_f32_e32 v182, v182
	v_rcp_f32_e32 v183, v183
	v_pk_mul_f32 v[52:53], v[52:53], v[176:177]
	v_pk_mul_f32 v[54:55], v[54:55], v[178:179]
	v_pk_mul_f32 v[48:49], v[48:49], v[180:181]
	v_pk_mul_f32 v[50:51], v[50:51], v[182:183]
	v_pk_fma_f32 v[184:185], v[52:53], v[52:53], v[184:185]
	v_pk_fma_f32 v[184:185], v[54:55], v[54:55], v[184:185]
	v_pk_fma_f32 v[184:185], v[48:49], v[48:49], v[184:185]
	v_pk_fma_f32 v[184:185], v[50:51], v[50:51], v[184:185]
	v_cvt_pk_bf16_f32 v52, v52, v53
	v_cvt_pk_bf16_f32 v53, v54, v55
	v_cvt_pk_bf16_f32 v54, v48, v49
	v_cvt_pk_bf16_f32 v55, v50, v51
	global_store_dwordx4 v143, v[52:55], s[96:97] offset:256
	s_cmp_lt_i32 s0, 8
	s_cbranch_scc1 .Le2_skip4
	v_add_f32_e32 v184, v184, v185
	ds_bpermute_b32 v173, v169, v184
	s_waitcnt lgkmcnt(0)
	v_add_f32_e32 v184, v184, v173
	ds_bpermute_b32 v173, v171, v184
	s_waitcnt lgkmcnt(0)
	v_add_f32_e32 v184, v184, v173
	s_mov_b64 exec, s[8:9]
	global_atomic_add_f32 v145, v184, s[4:5] offset:512
	s_mov_b64 exec, -1
.Le2_skip4:
	v_pk_mul_f32 v[44:45], v[44:45], v[158:159] op_sel:[0,1] op_sel_hi:[1,1]
	v_pk_mul_f32 v[46:47], v[46:47], v[158:159] op_sel:[0,1] op_sel_hi:[1,1]
	v_pk_mul_f32 v[40:41], v[40:41], v[158:159] op_sel:[0,1] op_sel_hi:[1,1]
	v_pk_mul_f32 v[42:43], v[42:43], v[158:159] op_sel:[0,1] op_sel_hi:[1,1]
	v_pk_mul_f32 v[176:177], v[44:45], v[44:45]
	v_pk_mul_f32 v[178:179], v[46:47], v[46:47]
	v_pk_mul_f32 v[180:181], v[40:41], v[40:41]
	v_pk_mul_f32 v[182:183], v[42:43], v[42:43]
	v_pk_fma_f32 v[176:177], v[176:177], v[140:141], v[142:143] op_sel_hi:[1,0,0]
	v_pk_fma_f32 v[178:179], v[178:179], v[140:141], v[142:143] op_sel_hi:[1,0,0]
	v_pk_fma_f32 v[180:181], v[180:181], v[140:141], v[142:143] op_sel_hi:[1,0,0]
	v_pk_fma_f32 v[182:183], v[182:183], v[140:141], v[142:143] op_sel_hi:[1,0,0]
	v_pk_mul_f32 v[176:177], v[44:45], v[176:177]
	v_pk_mul_f32 v[178:179], v[46:47], v[178:179]
	v_pk_mul_f32 v[180:181], v[40:41], v[180:181]
	v_pk_mul_f32 v[182:183], v[42:43], v[182:183]
	v_exp_f32_e32 v176, v176
	v_exp_f32_e32 v177, v177
	v_exp_f32_e32 v178, v178
	v_exp_f32_e32 v179, v179
	v_exp_f32_e32 v180, v180
	v_exp_f32_e32 v181, v181
	v_exp_f32_e32 v182, v182
	v_exp_f32_e32 v183, v183
	v_pk_add_f32 v[176:177], v[176:177], v[144:145] op_sel_hi:[1,0]
	v_pk_add_f32 v[178:179], v[178:179], v[144:145] op_sel_hi:[1,0]
	v_pk_add_f32 v[180:181], v[180:181], v[144:145] op_sel_hi:[1,0]
	v_pk_add_f32 v[182:183], v[182:183], v[144:145] op_sel_hi:[1,0]
	v_rcp_f32_e32 v176, v176
	v_rcp_f32_e32 v177, v177
	v_rcp_f32_e32 v178, v178
	v_rcp_f32_e32 v179, v179
	v_rcp_f32_e32 v180, v180
	v_rcp_f32_e32 v181, v181
	v_rcp_f32_e32 v182, v182
	v_rcp_f32_e32 v183, v183
	v_pk_mul_f32 v[44:45], v[44:45], v[176:177]
	v_pk_mul_f32 v[46:47], v[46:47], v[178:179]
	v_pk_mul_f32 v[40:41], v[40:41], v[180:181]
	v_pk_mul_f32 v[42:43], v[42:43], v[182:183]
	v_pk_mul_f32 v[184:185], v[44:45], v[44:45]
	v_pk_fma_f32 v[184:185], v[46:47], v[46:47], v[184:185]
	v_pk_fma_f32 v[184:185], v[40:41], v[40:41], v[184:185]
	v_pk_fma_f32 v[184:185], v[42:43], v[42:43], v[184:185]
	v_cvt_pk_bf16_f32 v44, v44, v45
	v_cvt_pk_bf16_f32 v45, v46, v47
	v_cvt_pk_bf16_f32 v46, v40, v41
	v_cvt_pk_bf16_f32 v47, v42, v43
	v_add_u32_e32 v143, 0x120000, v141
	global_store_dwordx4 v143, v[44:47], s[96:97]
	v_pk_mul_f32 v[36:37], v[36:37], v[158:159] op_sel:[0,1] op_sel_hi:[1,1]
	v_pk_mul_f32 v[38:39], v[38:39], v[158:159] op_sel:[0,1] op_sel_hi:[1,1]
	v_pk_mul_f32 v[32:33], v[32:33], v[158:159] op_sel:[0,1] op_sel_hi:[1,1]
	v_pk_mul_f32 v[34:35], v[34:35], v[158:159] op_sel:[0,1] op_sel_hi:[1,1]
	v_pk_mul_f32 v[176:177], v[36:37], v[36:37]
	v_pk_mul_f32 v[178:179], v[38:39], v[38:39]
	v_pk_mul_f32 v[180:181], v[32:33], v[32:33]
	v_pk_mul_f32 v[182:183], v[34:35], v[34:35]
	v_pk_fma_f32 v[176:177], v[176:177], v[140:141], v[142:143] op_sel_hi:[1,0,0]
	v_pk_fma_f32 v[178:179], v[178:179], v[140:141], v[142:143] op_sel_hi:[1,0,0]
	v_pk_fma_f32 v[180:181], v[180:181], v[140:141], v[142:143] op_sel_hi:[1,0,0]
	v_pk_fma_f32 v[182:183], v[182:183], v[140:141], v[142:143] op_sel_hi:[1,0,0]
	v_pk_mul_f32 v[176:177], v[36:37], v[176:177]
	v_pk_mul_f32 v[178:179], v[38:39], v[178:179]
	v_pk_mul_f32 v[180:181], v[32:33], v[180:181]
	v_pk_mul_f32 v[182:183], v[34:35], v[182:183]
	v_exp_f32_e32 v176, v176
	v_exp_f32_e32 v177, v177
	v_exp_f32_e32 v178, v178
	v_exp_f32_e32 v179, v179
	v_exp_f32_e32 v180, v180
	v_exp_f32_e32 v181, v181
	v_exp_f32_e32 v182, v182
	v_exp_f32_e32 v183, v183
	v_pk_add_f32 v[176:177], v[176:177], v[144:145] op_sel_hi:[1,0]
	v_pk_add_f32 v[178:179], v[178:179], v[144:145] op_sel_hi:[1,0]
	v_pk_add_f32 v[180:181], v[180:181], v[144:145] op_sel_hi:[1,0]
	v_pk_add_f32 v[182:183], v[182:183], v[144:145] op_sel_hi:[1,0]
	v_rcp_f32_e32 v176, v176
	v_rcp_f32_e32 v177, v177
	v_rcp_f32_e32 v178, v178
	v_rcp_f32_e32 v179, v179
	v_rcp_f32_e32 v180, v180
	v_rcp_f32_e32 v181, v181
	v_rcp_f32_e32 v182, v182
	v_rcp_f32_e32 v183, v183
	v_pk_mul_f32 v[36:37], v[36:37], v[176:177]
	v_pk_mul_f32 v[38:39], v[38:39], v[178:179]
	v_pk_mul_f32 v[32:33], v[32:33], v[180:181]
	v_pk_mul_f32 v[34:35], v[34:35], v[182:183]
	v_pk_fma_f32 v[184:185], v[36:37], v[36:37], v[184:185]
	v_pk_fma_f32 v[184:185], v[38:39], v[38:39], v[184:185]
	v_pk_fma_f32 v[184:185], v[32:33], v[32:33], v[184:185]
	v_pk_fma_f32 v[184:185], v[34:35], v[34:35], v[184:185]
	v_cvt_pk_bf16_f32 v36, v36, v37
	v_cvt_pk_bf16_f32 v37, v38, v39
	v_cvt_pk_bf16_f32 v38, v32, v33
	v_cvt_pk_bf16_f32 v39, v34, v35
	global_store_dwordx4 v143, v[36:39], s[96:97] offset:256
	s_cmp_lt_i32 s0, 8
	s_cbranch_scc1 .Le2_skip5
	v_add_f32_e32 v184, v184, v185
	ds_bpermute_b32 v173, v169, v184
	s_waitcnt lgkmcnt(0)
	v_add_f32_e32 v184, v184, v173
	ds_bpermute_b32 v173, v171, v184
	s_waitcnt lgkmcnt(0)
	v_add_f32_e32 v184, v184, v173
	s_mov_b64 exec, s[8:9]
	global_atomic_add_f32 v145, v184, s[4:5] offset:576
	s_mov_b64 exec, -1
.Le2_skip5:
	v_pk_mul_f32 v[28:29], v[28:29], v[160:161] op_sel:[0,0] op_sel_hi:[1,0]
	v_pk_mul_f32 v[30:31], v[30:31], v[160:161] op_sel:[0,0] op_sel_hi:[1,0]
	v_pk_mul_f32 v[24:25], v[24:25], v[160:161] op_sel:[0,0] op_sel_hi:[1,0]
	v_pk_mul_f32 v[26:27], v[26:27], v[160:161] op_sel:[0,0] op_sel_hi:[1,0]
	v_pk_mul_f32 v[176:177], v[28:29], v[28:29]
	v_pk_mul_f32 v[178:179], v[30:31], v[30:31]
	v_pk_mul_f32 v[180:181], v[24:25], v[24:25]
	v_pk_mul_f32 v[182:183], v[26:27], v[26:27]
	v_pk_fma_f32 v[176:177], v[176:177], v[140:141], v[142:143] op_sel_hi:[1,0,0]
	v_pk_fma_f32 v[178:179], v[178:179], v[140:141], v[142:143] op_sel_hi:[1,0,0]
	v_pk_fma_f32 v[180:181], v[180:181], v[140:141], v[142:143] op_sel_hi:[1,0,0]
	v_pk_fma_f32 v[182:183], v[182:183], v[140:141], v[142:143] op_sel_hi:[1,0,0]
	v_pk_mul_f32 v[176:177], v[28:29], v[176:177]
	v_pk_mul_f32 v[178:179], v[30:31], v[178:179]
	v_pk_mul_f32 v[180:181], v[24:25], v[180:181]
	v_pk_mul_f32 v[182:183], v[26:27], v[182:183]
	v_exp_f32_e32 v176, v176
	v_exp_f32_e32 v177, v177
	v_exp_f32_e32 v178, v178
	v_exp_f32_e32 v179, v179
	v_exp_f32_e32 v180, v180
	v_exp_f32_e32 v181, v181
	v_exp_f32_e32 v182, v182
	v_exp_f32_e32 v183, v183
	v_pk_add_f32 v[176:177], v[176:177], v[144:145] op_sel_hi:[1,0]
	v_pk_add_f32 v[178:179], v[178:179], v[144:145] op_sel_hi:[1,0]
	v_pk_add_f32 v[180:181], v[180:181], v[144:145] op_sel_hi:[1,0]
	v_pk_add_f32 v[182:183], v[182:183], v[144:145] op_sel_hi:[1,0]
	v_rcp_f32_e32 v176, v176
	v_rcp_f32_e32 v177, v177
	v_rcp_f32_e32 v178, v178
	v_rcp_f32_e32 v179, v179
	v_rcp_f32_e32 v180, v180
	v_rcp_f32_e32 v181, v181
	v_rcp_f32_e32 v182, v182
	v_rcp_f32_e32 v183, v183
	v_pk_mul_f32 v[28:29], v[28:29], v[176:177]
	v_pk_mul_f32 v[30:31], v[30:31], v[178:179]
	v_pk_mul_f32 v[24:25], v[24:25], v[180:181]
	v_pk_mul_f32 v[26:27], v[26:27], v[182:183]
	v_pk_mul_f32 v[184:185], v[28:29], v[28:29]
	v_pk_fma_f32 v[184:185], v[30:31], v[30:31], v[184:185]
	v_pk_fma_f32 v[184:185], v[24:25], v[24:25], v[184:185]
	v_pk_fma_f32 v[184:185], v[26:27], v[26:27], v[184:185]
	v_cvt_pk_bf16_f32 v28, v28, v29
	v_cvt_pk_bf16_f32 v29, v30, v31
	v_cvt_pk_bf16_f32 v30, v24, v25
	v_cvt_pk_bf16_f32 v31, v26, v27
	v_add_u32_e32 v143, 0x140000, v141
	global_store_dwordx4 v143, v[28:31], s[96:97]
	v_pk_mul_f32 v[20:21], v[20:21], v[160:161] op_sel:[0,0] op_sel_hi:[1,0]
	v_pk_mul_f32 v[22:23], v[22:23], v[160:161] op_sel:[0,0] op_sel_hi:[1,0]
	v_pk_mul_f32 v[16:17], v[16:17], v[160:161] op_sel:[0,0] op_sel_hi:[1,0]
	v_pk_mul_f32 v[18:19], v[18:19], v[160:161] op_sel:[0,0] op_sel_hi:[1,0]
	v_pk_mul_f32 v[176:177], v[20:21], v[20:21]
	v_pk_mul_f32 v[178:179], v[22:23], v[22:23]
	v_pk_mul_f32 v[180:181], v[16:17], v[16:17]
	v_pk_mul_f32 v[182:183], v[18:19], v[18:19]
	v_pk_fma_f32 v[176:177], v[176:177], v[140:141], v[142:143] op_sel_hi:[1,0,0]
	v_pk_fma_f32 v[178:179], v[178:179], v[140:141], v[142:143] op_sel_hi:[1,0,0]
	v_pk_fma_f32 v[180:181], v[180:181], v[140:141], v[142:143] op_sel_hi:[1,0,0]
	v_pk_fma_f32 v[182:183], v[182:183], v[140:141], v[142:143] op_sel_hi:[1,0,0]
	v_pk_mul_f32 v[176:177], v[20:21], v[176:177]
	v_pk_mul_f32 v[178:179], v[22:23], v[178:179]
	v_pk_mul_f32 v[180:181], v[16:17], v[180:181]
	v_pk_mul_f32 v[182:183], v[18:19], v[182:183]
	v_exp_f32_e32 v176, v176
	v_exp_f32_e32 v177, v177
	v_exp_f32_e32 v178, v178
	v_exp_f32_e32 v179, v179
	v_exp_f32_e32 v180, v180
	v_exp_f32_e32 v181, v181
	v_exp_f32_e32 v182, v182
	v_exp_f32_e32 v183, v183
	v_pk_add_f32 v[176:177], v[176:177], v[144:145] op_sel_hi:[1,0]
	v_pk_add_f32 v[178:179], v[178:179], v[144:145] op_sel_hi:[1,0]
	v_pk_add_f32 v[180:181], v[180:181], v[144:145] op_sel_hi:[1,0]
	v_pk_add_f32 v[182:183], v[182:183], v[144:145] op_sel_hi:[1,0]
	v_rcp_f32_e32 v176, v176
	v_rcp_f32_e32 v177, v177
	v_rcp_f32_e32 v178, v178
	v_rcp_f32_e32 v179, v179
	v_rcp_f32_e32 v180, v180
	v_rcp_f32_e32 v181, v181
	v_rcp_f32_e32 v182, v182
	v_rcp_f32_e32 v183, v183
	v_pk_mul_f32 v[20:21], v[20:21], v[176:177]
	v_pk_mul_f32 v[22:23], v[22:23], v[178:179]
	v_pk_mul_f32 v[16:17], v[16:17], v[180:181]
	v_pk_mul_f32 v[18:19], v[18:19], v[182:183]
	v_pk_fma_f32 v[184:185], v[20:21], v[20:21], v[184:185]
	v_pk_fma_f32 v[184:185], v[22:23], v[22:23], v[184:185]
	v_pk_fma_f32 v[184:185], v[16:17], v[16:17], v[184:185]
	v_pk_fma_f32 v[184:185], v[18:19], v[18:19], v[184:185]
	v_cvt_pk_bf16_f32 v20, v20, v21
	v_cvt_pk_bf16_f32 v21, v22, v23
	v_cvt_pk_bf16_f32 v22, v16, v17
	v_cvt_pk_bf16_f32 v23, v18, v19
	global_store_dwordx4 v143, v[20:23], s[96:97] offset:256
	s_cmp_lt_i32 s0, 8
	s_cbranch_scc1 .Le2_skip6
	v_add_f32_e32 v184, v184, v185
	ds_bpermute_b32 v173, v169, v184
	s_waitcnt lgkmcnt(0)
	v_add_f32_e32 v184, v184, v173
	ds_bpermute_b32 v173, v171, v184
	s_waitcnt lgkmcnt(0)
	v_add_f32_e32 v184, v184, v173
	s_mov_b64 exec, s[8:9]
	global_atomic_add_f32 v145, v184, s[4:5] offset:640
	s_mov_b64 exec, -1
.Le2_skip6:
	v_pk_mul_f32 v[12:13], v[12:13], v[160:161] op_sel:[0,1] op_sel_hi:[1,1]
	v_pk_mul_f32 v[14:15], v[14:15], v[160:161] op_sel:[0,1] op_sel_hi:[1,1]
	v_pk_mul_f32 v[8:9], v[8:9], v[160:161] op_sel:[0,1] op_sel_hi:[1,1]
	v_pk_mul_f32 v[10:11], v[10:11], v[160:161] op_sel:[0,1] op_sel_hi:[1,1]
	v_pk_mul_f32 v[176:177], v[12:13], v[12:13]
	v_pk_mul_f32 v[178:179], v[14:15], v[14:15]
	v_pk_mul_f32 v[180:181], v[8:9], v[8:9]
	v_pk_mul_f32 v[182:183], v[10:11], v[10:11]
	v_pk_fma_f32 v[176:177], v[176:177], v[140:141], v[142:143] op_sel_hi:[1,0,0]
	v_pk_fma_f32 v[178:179], v[178:179], v[140:141], v[142:143] op_sel_hi:[1,0,0]
	v_pk_fma_f32 v[180:181], v[180:181], v[140:141], v[142:143] op_sel_hi:[1,0,0]
	v_pk_fma_f32 v[182:183], v[182:183], v[140:141], v[142:143] op_sel_hi:[1,0,0]
	v_pk_mul_f32 v[176:177], v[12:13], v[176:177]
	v_pk_mul_f32 v[178:179], v[14:15], v[178:179]
	v_pk_mul_f32 v[180:181], v[8:9], v[180:181]
	v_pk_mul_f32 v[182:183], v[10:11], v[182:183]
	v_exp_f32_e32 v176, v176
	v_exp_f32_e32 v177, v177
	v_exp_f32_e32 v178, v178
	v_exp_f32_e32 v179, v179
	v_exp_f32_e32 v180, v180
	v_exp_f32_e32 v181, v181
	v_exp_f32_e32 v182, v182
	v_exp_f32_e32 v183, v183
	v_pk_add_f32 v[176:177], v[176:177], v[144:145] op_sel_hi:[1,0]
	v_pk_add_f32 v[178:179], v[178:179], v[144:145] op_sel_hi:[1,0]
	v_pk_add_f32 v[180:181], v[180:181], v[144:145] op_sel_hi:[1,0]
	v_pk_add_f32 v[182:183], v[182:183], v[144:145] op_sel_hi:[1,0]
	v_rcp_f32_e32 v176, v176
	v_rcp_f32_e32 v177, v177
	v_rcp_f32_e32 v178, v178
	v_rcp_f32_e32 v179, v179
	v_rcp_f32_e32 v180, v180
	v_rcp_f32_e32 v181, v181
	v_rcp_f32_e32 v182, v182
	v_rcp_f32_e32 v183, v183
	v_pk_mul_f32 v[12:13], v[12:13], v[176:177]
	v_pk_mul_f32 v[14:15], v[14:15], v[178:179]
	v_pk_mul_f32 v[8:9], v[8:9], v[180:181]
	v_pk_mul_f32 v[10:11], v[10:11], v[182:183]
	v_pk_mul_f32 v[184:185], v[12:13], v[12:13]
	v_pk_fma_f32 v[184:185], v[14:15], v[14:15], v[184:185]
	v_pk_fma_f32 v[184:185], v[8:9], v[8:9], v[184:185]
	v_pk_fma_f32 v[184:185], v[10:11], v[10:11], v[184:185]
	v_cvt_pk_bf16_f32 v12, v12, v13
	v_cvt_pk_bf16_f32 v13, v14, v15
	v_cvt_pk_bf16_f32 v14, v8, v9
	v_cvt_pk_bf16_f32 v15, v10, v11
	v_add_u32_e32 v143, 0x160000, v141
	global_store_dwordx4 v143, v[12:15], s[96:97]
	v_pk_mul_f32 v[4:5], v[4:5], v[160:161] op_sel:[0,1] op_sel_hi:[1,1]
	v_pk_mul_f32 v[6:7], v[6:7], v[160:161] op_sel:[0,1] op_sel_hi:[1,1]
	v_pk_mul_f32 v[0:1], v[0:1], v[160:161] op_sel:[0,1] op_sel_hi:[1,1]
	v_pk_mul_f32 v[2:3], v[2:3], v[160:161] op_sel:[0,1] op_sel_hi:[1,1]
	v_pk_mul_f32 v[176:177], v[4:5], v[4:5]
	v_pk_mul_f32 v[178:179], v[6:7], v[6:7]
	v_pk_mul_f32 v[180:181], v[0:1], v[0:1]
	v_pk_mul_f32 v[182:183], v[2:3], v[2:3]
	v_pk_fma_f32 v[176:177], v[176:177], v[140:141], v[142:143] op_sel_hi:[1,0,0]
	v_pk_fma_f32 v[178:179], v[178:179], v[140:141], v[142:143] op_sel_hi:[1,0,0]
	v_pk_fma_f32 v[180:181], v[180:181], v[140:141], v[142:143] op_sel_hi:[1,0,0]
	v_pk_fma_f32 v[182:183], v[182:183], v[140:141], v[142:143] op_sel_hi:[1,0,0]
	v_pk_mul_f32 v[176:177], v[4:5], v[176:177]
	v_pk_mul_f32 v[178:179], v[6:7], v[178:179]
	v_pk_mul_f32 v[180:181], v[0:1], v[180:181]
	v_pk_mul_f32 v[182:183], v[2:3], v[182:183]
	v_exp_f32_e32 v176, v176
	v_exp_f32_e32 v177, v177
	v_exp_f32_e32 v178, v178
	v_exp_f32_e32 v179, v179
	v_exp_f32_e32 v180, v180
	v_exp_f32_e32 v181, v181
	v_exp_f32_e32 v182, v182
	v_exp_f32_e32 v183, v183
	v_pk_add_f32 v[176:177], v[176:177], v[144:145] op_sel_hi:[1,0]
	v_pk_add_f32 v[178:179], v[178:179], v[144:145] op_sel_hi:[1,0]
	v_pk_add_f32 v[180:181], v[180:181], v[144:145] op_sel_hi:[1,0]
	v_pk_add_f32 v[182:183], v[182:183], v[144:145] op_sel_hi:[1,0]
	v_rcp_f32_e32 v176, v176
	v_rcp_f32_e32 v177, v177
	v_rcp_f32_e32 v178, v178
	v_rcp_f32_e32 v179, v179
	v_rcp_f32_e32 v180, v180
	v_rcp_f32_e32 v181, v181
	v_rcp_f32_e32 v182, v182
	v_rcp_f32_e32 v183, v183
	v_pk_mul_f32 v[4:5], v[4:5], v[176:177]
	v_pk_mul_f32 v[6:7], v[6:7], v[178:179]
	v_pk_mul_f32 v[0:1], v[0:1], v[180:181]
	v_pk_mul_f32 v[2:3], v[2:3], v[182:183]
	v_pk_fma_f32 v[184:185], v[4:5], v[4:5], v[184:185]
	v_pk_fma_f32 v[184:185], v[6:7], v[6:7], v[184:185]
	v_pk_fma_f32 v[184:185], v[0:1], v[0:1], v[184:185]
	v_pk_fma_f32 v[184:185], v[2:3], v[2:3], v[184:185]
	v_cvt_pk_bf16_f32 v4, v4, v5
	v_cvt_pk_bf16_f32 v5, v6, v7
	v_cvt_pk_bf16_f32 v6, v0, v1
	v_cvt_pk_bf16_f32 v7, v2, v3
	global_store_dwordx4 v143, v[4:7], s[96:97] offset:256
	s_cmp_lt_i32 s0, 8
	s_cbranch_scc1 .Le2_skip7
	v_add_f32_e32 v184, v184, v185
	ds_bpermute_b32 v173, v169, v184
	s_waitcnt lgkmcnt(0)
	v_add_f32_e32 v184, v184, v173
	ds_bpermute_b32 v173, v171, v184
	s_waitcnt lgkmcnt(0)
	v_add_f32_e32 v184, v184, v173
	s_mov_b64 exec, s[8:9]
	global_atomic_add_f32 v145, v184, s[4:5] offset:704
	s_mov_b64 exec, -1
.Le2_skip7:
	s_branch .LBB0_591
